# diff-attention tile loops: running maximum kept in v213, all three leading V operands read right after Q.K^T, P.V MFMAs 1-3 back to back with row-max/threshold in their shadows
# speedup vs baseline: 1.0018x; 1.0018x over previous
.LBB0_280:
	v_sub_f32_e32 v0, v18, v186
	v_exp_f32_e32 v0, v0
	v_sub_f32_e32 v18, v19, v186
	v_exp_f32_e32 v18, v18
	v_sub_f32_e32 v19, v20, v186
	v_exp_f32_e32 v19, v19
	v_sub_f32_e32 v20, v21, v186
	v_exp_f32_e32 v20, v20
	v_sub_f32_e32 v22, v22, v186
	v_add_f32_e32 v21, 0, v0
	v_exp_f32_e32 v22, v22
	v_sub_f32_e32 v23, v23, v186
	v_add_f32_e32 v21, v18, v21
	v_exp_f32_e32 v23, v23
	v_sub_f32_e32 v24, v24, v186
	v_add_f32_e32 v21, v19, v21
	v_exp_f32_e32 v24, v24
	v_sub_f32_e32 v25, v25, v186
	v_add_f32_e32 v21, v20, v21
	v_exp_f32_e32 v25, v25
	v_sub_f32_e32 v26, v26, v186
	v_add_f32_e32 v21, v22, v21
	v_exp_f32_e32 v26, v26
	v_sub_f32_e32 v27, v27, v186
	v_add_f32_e32 v21, v23, v21
	v_exp_f32_e32 v27, v27
	v_sub_f32_e32 v28, v28, v186
	v_add_f32_e32 v21, v24, v21
	v_exp_f32_e32 v28, v28
	v_sub_f32_e32 v29, v29, v186
	v_add_f32_e32 v21, v25, v21
	v_exp_f32_e32 v29, v29
	v_sub_f32_e32 v30, v30, v186
	v_add_f32_e32 v21, v26, v21
	v_exp_f32_e32 v30, v30
	v_sub_f32_e32 v31, v31, v186
	v_add_f32_e32 v21, v27, v21
	v_exp_f32_e32 v31, v31
	v_sub_f32_e32 v32, v32, v186
	v_add_f32_e32 v21, v28, v21
	v_exp_f32_e32 v32, v32
	v_sub_f32_e32 v33, v33, v186
	v_add_f32_e32 v21, v29, v21
	v_exp_f32_e32 v33, v33
	v_add_f32_e32 v21, v30, v21
	v_add_f32_e32 v21, v31, v21
	v_cvt_pk_bf16_f32 v182, v0, v18
	v_add_u32_e32 v0, s3, v242
	v_add_f32_e32 v21, v32, v21
	v_cvt_pk_bf16_f32 v183, v19, v20
	v_lshlrev_b64 v[18:19], 9, v[0:1]
	v_add_u32_e32 v0, s3, v243
	v_add_f32_e32 v203, v33, v21
	v_lshl_add_u64 v[204:205], v[40:41], 0, v[18:19]
	v_lshlrev_b64 v[18:19], 9, v[0:1]
	s_lshl_b32 s43, s2, 2
	v_cvt_pk_bf16_f32 v178, v26, v27
	v_cvt_pk_bf16_f32 v179, v28, v29
	v_cvt_pk_bf16_f32 v180, v30, v31
	v_cvt_pk_bf16_f32 v181, v32, v33
	v_cvt_pk_bf16_f32 v184, v22, v23
	v_cvt_pk_bf16_f32 v185, v24, v25
	v_fmac_f32_e32 v203, 0, v42
	v_lshl_add_u64 v[206:207], v[38:39], 0, v[18:19]
	v_lshl_add_u64 v[208:209], v[36:37], 0, s[18:19]
	v_lshl_add_u64 v[210:211], v[34:35], 0, s[18:19]
	v_mov_b64_e32 v[32:33], v[16:17]
	v_mov_b64_e32 v[48:49], v[16:17]
	v_mov_b64_e32 v[64:65], v[16:17]
	v_mov_b64_e32 v[80:81], v[16:17]
	v_mov_b64_e32 v[96:97], v[16:17]
	v_mov_b64_e32 v[112:113], v[16:17]
	v_mov_b64_e32 v[128:129], v[16:17]
	s_add_i32 s44, s43, 4
	s_add_i32 s45, s33, 0x60
	s_mov_b32 s0, 1
	s_mov_b32 s46, 0
	s_mov_b32 s47, 3
	v_mov_b64_e32 v[30:31], v[14:15]
	v_mov_b64_e32 v[28:29], v[12:13]
	v_mov_b64_e32 v[26:27], v[10:11]
	v_mov_b64_e32 v[24:25], v[8:9]
	v_mov_b64_e32 v[22:23], v[6:7]
	v_mov_b64_e32 v[20:21], v[4:5]
	v_mov_b64_e32 v[18:19], v[2:3]
	v_mov_b64_e32 v[46:47], v[14:15]
	v_mov_b64_e32 v[44:45], v[12:13]
	v_mov_b64_e32 v[42:43], v[10:11]
	v_mov_b64_e32 v[40:41], v[8:9]
	v_mov_b64_e32 v[38:39], v[6:7]
	v_mov_b64_e32 v[36:37], v[4:5]
	v_mov_b64_e32 v[34:35], v[2:3]
	v_mov_b64_e32 v[62:63], v[14:15]
	v_mov_b64_e32 v[60:61], v[12:13]
	v_mov_b64_e32 v[58:59], v[10:11]
	v_mov_b64_e32 v[56:57], v[8:9]
	v_mov_b64_e32 v[54:55], v[6:7]
	v_mov_b64_e32 v[52:53], v[4:5]
	v_mov_b64_e32 v[50:51], v[2:3]
	v_mov_b64_e32 v[78:79], v[14:15]
	v_mov_b64_e32 v[76:77], v[12:13]
	v_mov_b64_e32 v[74:75], v[10:11]
	v_mov_b64_e32 v[72:73], v[8:9]
	v_mov_b64_e32 v[70:71], v[6:7]
	v_mov_b64_e32 v[68:69], v[4:5]
	v_mov_b64_e32 v[66:67], v[2:3]
	v_mov_b64_e32 v[94:95], v[14:15]
	v_mov_b64_e32 v[92:93], v[12:13]
	v_mov_b64_e32 v[90:91], v[10:11]
	v_mov_b64_e32 v[88:89], v[8:9]
	v_mov_b64_e32 v[86:87], v[6:7]
	v_mov_b64_e32 v[84:85], v[4:5]
	v_mov_b64_e32 v[82:83], v[2:3]
	v_mov_b64_e32 v[110:111], v[14:15]
	v_mov_b64_e32 v[108:109], v[12:13]
	v_mov_b64_e32 v[106:107], v[10:11]
	v_mov_b64_e32 v[104:105], v[8:9]
	v_mov_b64_e32 v[102:103], v[6:7]
	v_mov_b64_e32 v[100:101], v[4:5]
	v_mov_b64_e32 v[98:99], v[2:3]
	v_mov_b64_e32 v[126:127], v[14:15]
	v_mov_b64_e32 v[124:125], v[12:13]
	v_mov_b64_e32 v[122:123], v[10:11]
	v_mov_b64_e32 v[120:121], v[8:9]
	v_mov_b64_e32 v[118:119], v[6:7]
	v_mov_b64_e32 v[116:117], v[4:5]
	v_mov_b64_e32 v[114:115], v[2:3]
	s_mov_b32 s49, 0
	v_mov_b32_e32 v213, v186

.Lmy_a_nok2:
	s_waitcnt lgkmcnt(2)
	v_mfma_f32_32x32x16_bf16 v[130:145], v[248:251], v[166:169], v[130:145]
	s_waitcnt lgkmcnt(1)
	v_mfma_f32_32x32x16_bf16 v[130:145], v[214:217], v[170:173], v[130:145]
	s_waitcnt lgkmcnt(0)
	v_mfma_f32_32x32x16_bf16 v[130:145], v[188:191], v[174:177], v[130:145]
	s_lshl_b32 s3, s49, 14
	v_add_u32_e32 v252, s3, v224
	v_add_u32_e32 v253, s3, v228
	ds_read_b64_tr_b16 v[190:191], v252 offset:49152
	ds_read_b64_tr_b16 v[192:193], v252 offset:53248
	ds_read_b64_tr_b16 v[248:249], v253 offset:49152
	ds_read_b64_tr_b16 v[250:251], v253 offset:53248
	v_add_u32_e32 v254, s3, v229
	ds_read_b64_tr_b16 v[186:187], v254 offset:49152
	ds_read_b64_tr_b16 v[188:189], v254 offset:53248
	s_cmp_lt_u32 s0, s43
	s_cbranch_scc1 .LBB0_293
	v_add_u32_e32 v0, s46, v223
	v_add_u32_e32 v214, 32, v0
	v_cmp_lt_u32_e32 vcc, v214, v201
	s_nop 1
	v_cndmask_b32_e32 v131, v246, v131, vcc
	v_cmp_le_u32_e32 vcc, v214, v201
	v_add_u32_e32 v214, 34, v0
	s_nop 0
	v_cndmask_b32_e32 v130, v246, v130, vcc
	v_cmp_le_u32_e32 vcc, v214, v201
	v_add_u32_e32 v214, 35, v0
	s_nop 0
	v_cndmask_b32_e32 v132, v246, v132, vcc
	v_cmp_le_u32_e32 vcc, v214, v201
	v_add_u32_e32 v214, 40, v0
	s_nop 0
	v_cndmask_b32_e32 v133, v246, v133, vcc
	v_cmp_le_u32_e32 vcc, v214, v201
	v_add_u32_e32 v214, 41, v0
	s_nop 0
	v_cndmask_b32_e32 v134, v246, v134, vcc
	v_cmp_le_u32_e32 vcc, v214, v201
	v_add_u32_e32 v214, 42, v0
	s_nop 0
	v_cndmask_b32_e32 v135, v246, v135, vcc
	v_cmp_le_u32_e32 vcc, v214, v201
	v_add_u32_e32 v214, 43, v0
	s_nop 0
	v_cndmask_b32_e32 v136, v246, v136, vcc
	v_cmp_le_u32_e32 vcc, v214, v201
	v_add_u32_e32 v214, 48, v0
	s_nop 0
	v_cndmask_b32_e32 v137, v246, v137, vcc
	v_cmp_le_u32_e32 vcc, v214, v201
	v_add_u32_e32 v214, 49, v0
	s_nop 0
	v_cndmask_b32_e32 v138, v246, v138, vcc
	v_cmp_le_u32_e32 vcc, v214, v201
	v_add_u32_e32 v214, 50, v0
	s_nop 0
	v_cndmask_b32_e32 v139, v246, v139, vcc
	v_cmp_le_u32_e32 vcc, v214, v201
	v_add_u32_e32 v214, 51, v0
	s_nop 0
	v_cndmask_b32_e32 v140, v246, v140, vcc
	v_cmp_le_u32_e32 vcc, v214, v201
	v_add_u32_e32 v214, 56, v0
	s_nop 0
	v_cndmask_b32_e32 v141, v246, v141, vcc
	v_cmp_le_u32_e32 vcc, v214, v201
	v_add_u32_e32 v214, 57, v0
	s_nop 0
	v_cndmask_b32_e32 v142, v246, v142, vcc
	v_cmp_le_u32_e32 vcc, v214, v201
	v_add_u32_e32 v214, 58, v0
	v_add_u32_e32 v0, 59, v0
	v_cndmask_b32_e32 v143, v246, v143, vcc
	v_cmp_le_u32_e32 vcc, v214, v201
	s_nop 1
	v_cndmask_b32_e32 v144, v246, v144, vcc
	v_cmp_le_u32_e32 vcc, v0, v201
	s_nop 1
	v_cndmask_b32_e32 v145, v246, v145, vcc
.LBB0_293:
	s_waitcnt lgkmcnt(4)
	v_mfma_f32_32x32x16_bf16 v[114:129], v[182:185], v[190:193], v[114:129]
	v_add_u32_e32 v195, s3, v230
	ds_read_b64_tr_b16 v[190:191], v195 offset:49152
	ds_read_b64_tr_b16 v[192:193], v195 offset:53248
	v_max3_f32 v0, v130, v131, v132
	v_max3_f32 v214, v133, v134, v135
	v_max3_f32 v215, v136, v137, v138
	v_max3_f32 v216, v139, v140, v141
	s_waitcnt lgkmcnt(4)
	v_mfma_f32_32x32x16_bf16 v[98:113], v[182:185], v[248:251], v[98:113]
	ds_read_b64_tr_b16 v[248:249], v252 offset:49408
	ds_read_b64_tr_b16 v[250:251], v252 offset:53504
	v_max3_f32 v0, v0, v142, v143
	v_max3_f32 v214, v214, v144, v145
	v_max3_f32 v0, v0, v214, v215
	v_max_f32_e32 v0, v0, v216
	v_mov_b32_e32 v214, v0
	s_nop 1
	v_permlane32_swap_b32_e32 v0, v214
	v_max_f32_e32 v0, v0, v214
	s_waitcnt lgkmcnt(4)
	v_mfma_f32_32x32x16_bf16 v[82:97], v[182:185], v[186:189], v[82:97]
	ds_read_b64_tr_b16 v[186:187], v253 offset:49408
	ds_read_b64_tr_b16 v[188:189], v253 offset:53504
	v_add_f32_e32 v214, 0x41000000, v213
	v_cmp_gt_f32_e32 vcc, v0, v214
	s_cmp_eq_u64 vcc, 0
	v_max_f32_e32 v0, v213, v0
	s_cselect_b64 s[0:1], -1, 0
	v_cndmask_b32_e64 v0, v0, v213, s[0:1]
	v_sub_f32_e32 v247, v213, v0
	v_exp_f32_e32 v247, v247
	s_waitcnt lgkmcnt(4)
	v_mfma_f32_32x32x16_bf16 v[66:81], v[182:185], v[190:193], v[66:81]
	ds_read_b64_tr_b16 v[190:191], v254 offset:49408
	ds_read_b64_tr_b16 v[192:193], v254 offset:53504
	v_sub_f32_e32 v130, v130, v0
	v_exp_f32_e32 v1, v130
	v_sub_f32_e32 v131, v131, v0
	v_exp_f32_e32 v131, v131
	v_add_f32_e32 v130, 0, v1
	s_cmp_le_u32 s47, s44
	s_cbranch_scc0 .Lmy_a_nov1
	s_mov_b32 m0, s54
	s_nop 0
	global_load_lds_dwordx4 v[206:207], off
.Lmy_a_nov1:
	s_waitcnt lgkmcnt(4)
	v_mfma_f32_32x32x16_bf16 v[50:65], v[182:185], v[248:251], v[50:65]
	ds_read_b64_tr_b16 v[248:249], v195 offset:49408
	ds_read_b64_tr_b16 v[250:251], v195 offset:53504
	v_sub_f32_e32 v132, v132, v0
	v_exp_f32_e32 v132, v132
	v_add_f32_e32 v130, v131, v130
	v_sub_f32_e32 v133, v133, v0
	v_exp_f32_e32 v133, v133
	v_add_f32_e32 v130, v132, v130
	s_waitcnt lgkmcnt(4)
	v_mfma_f32_32x32x16_bf16 v[34:49], v[182:185], v[186:189], v[34:49]
	ds_read_b64_tr_b16 v[186:187], v252 offset:57344
	ds_read_b64_tr_b16 v[188:189], v252 offset:61440
	v_sub_f32_e32 v134, v134, v0
	v_exp_f32_e32 v134, v134
	v_add_f32_e32 v130, v133, v130
	v_sub_f32_e32 v135, v135, v0
	v_exp_f32_e32 v135, v135
	v_add_f32_e32 v130, v134, v130
	s_waitcnt lgkmcnt(4)
	v_mfma_f32_32x32x16_bf16 v[18:33], v[182:185], v[190:193], v[18:33]
	ds_read_b64_tr_b16 v[190:191], v253 offset:57344
	ds_read_b64_tr_b16 v[192:193], v253 offset:61440
	v_sub_f32_e32 v136, v136, v0
	v_exp_f32_e32 v136, v136
	v_add_f32_e32 v130, v135, v130
	s_waitcnt lgkmcnt(4)
	v_mfma_f32_32x32x16_bf16 v[2:17], v[182:185], v[248:251], v[2:17]
	ds_read_b64_tr_b16 v[182:183], v254 offset:57344
	ds_read_b64_tr_b16 v[184:185], v254 offset:61440
	v_sub_f32_e32 v137, v137, v0
	v_exp_f32_e32 v137, v137
	v_add_f32_e32 v130, v136, v130
	s_waitcnt lgkmcnt(4)
	v_mfma_f32_32x32x16_bf16 v[114:129], v[178:181], v[186:189], v[114:129]
	ds_read_b64_tr_b16 v[248:249], v195 offset:57344
	ds_read_b64_tr_b16 v[250:251], v195 offset:61440
	v_sub_f32_e32 v138, v138, v0
	v_exp_f32_e32 v138, v138
	v_add_f32_e32 v130, v137, v130
	s_waitcnt lgkmcnt(4)
	v_mfma_f32_32x32x16_bf16 v[98:113], v[178:181], v[190:193], v[98:113]
	ds_read_b64_tr_b16 v[190:191], v252 offset:57600
	ds_read_b64_tr_b16 v[192:193], v252 offset:61696
	v_sub_f32_e32 v139, v139, v0
	v_exp_f32_e32 v139, v139
	v_add_f32_e32 v130, v138, v130
	s_cmp_le_u32 s47, s44
	s_cbranch_scc0 .Lmy_a_nov2
	s_mov_b32 m0, s55
	s_nop 0
	global_load_lds_dwordx4 v[204:205], off

.LBB0_295:
	v_add_f32_e32 v130, v145, v130
	s_add_i32 s0, s48, 1
	s_cmp_lg_u32 s48, 2
	s_cselect_b32 s0, s0, 0
	s_add_i32 s46, s46, 32
	s_add_i32 s47, s47, 1
	v_fmac_f32_e32 v130, v203, v247
	v_cvt_pk_bf16_f32 v182, v1, v131
	v_mov_b32_e32 v1, 0
	v_cvt_pk_bf16_f32 v183, v132, v133
	v_cvt_pk_bf16_f32 v184, v134, v135
	v_cvt_pk_bf16_f32 v185, v136, v137
	v_cvt_pk_bf16_f32 v178, v138, v139
	v_cvt_pk_bf16_f32 v179, v140, v141
	v_cvt_pk_bf16_f32 v180, v142, v143
	v_cvt_pk_bf16_f32 v181, v144, v145
	v_lshl_add_u64 v[204:205], v[204:205], 0, s[12:13]
	v_lshl_add_u64 v[206:207], v[206:207], 0, s[12:13]
	v_lshl_add_u64 v[208:209], v[208:209], 0, s[8:9]
	s_cmp_eq_u32 s45, s46
	v_lshl_add_u64 v[210:211], v[210:211], 0, s[8:9]
	s_cbranch_scc1 .LBB0_297
	v_mov_b32_e32 v203, v130
	v_mov_b32_e32 v213, v0
	s_mov_b32 s49, s48
	s_branch .LBB0_281

.LBB0_1604:
	v_sub_f32_e32 v0, v18, v186
	v_exp_f32_e32 v0, v0
	v_sub_f32_e32 v18, v19, v186
	v_exp_f32_e32 v18, v18
	v_sub_f32_e32 v19, v20, v186
	v_exp_f32_e32 v19, v19
	v_sub_f32_e32 v20, v21, v186
	v_exp_f32_e32 v20, v20
	v_sub_f32_e32 v22, v22, v186
	v_add_f32_e32 v21, 0, v0
	v_exp_f32_e32 v22, v22
	v_sub_f32_e32 v23, v23, v186
	v_add_f32_e32 v21, v18, v21
	v_exp_f32_e32 v23, v23
	v_sub_f32_e32 v24, v24, v186
	v_add_f32_e32 v21, v19, v21
	v_exp_f32_e32 v24, v24
	v_sub_f32_e32 v25, v25, v186
	v_add_f32_e32 v21, v20, v21
	v_exp_f32_e32 v25, v25
	v_sub_f32_e32 v26, v26, v186
	v_add_f32_e32 v21, v22, v21
	v_exp_f32_e32 v26, v26
	v_sub_f32_e32 v27, v27, v186
	v_add_f32_e32 v21, v23, v21
	v_exp_f32_e32 v27, v27
	v_sub_f32_e32 v28, v28, v186
	v_add_f32_e32 v21, v24, v21
	v_exp_f32_e32 v28, v28
	v_sub_f32_e32 v29, v29, v186
	v_add_f32_e32 v21, v25, v21
	v_exp_f32_e32 v29, v29
	v_sub_f32_e32 v30, v30, v186
	v_add_f32_e32 v21, v26, v21
	v_exp_f32_e32 v30, v30
	v_sub_f32_e32 v31, v31, v186
	v_add_f32_e32 v21, v27, v21
	v_exp_f32_e32 v31, v31
	v_sub_f32_e32 v32, v32, v186
	v_add_f32_e32 v21, v28, v21
	v_exp_f32_e32 v32, v32
	v_sub_f32_e32 v33, v33, v186
	v_add_f32_e32 v21, v29, v21
	v_exp_f32_e32 v33, v33
	v_add_f32_e32 v21, v30, v21
	v_add_f32_e32 v21, v31, v21
	v_cvt_pk_bf16_f32 v182, v0, v18
	v_add_u32_e32 v0, s3, v242
	v_add_f32_e32 v21, v32, v21
	v_cvt_pk_bf16_f32 v183, v19, v20
	v_lshlrev_b64 v[18:19], 9, v[0:1]
	v_add_u32_e32 v0, s3, v243
	v_add_f32_e32 v203, v33, v21
	v_lshl_add_u64 v[204:205], v[40:41], 0, v[18:19]
	v_lshlrev_b64 v[18:19], 9, v[0:1]
	s_lshl_b32 s41, s2, 2
	v_cvt_pk_bf16_f32 v178, v26, v27
	v_cvt_pk_bf16_f32 v179, v28, v29
	v_cvt_pk_bf16_f32 v180, v30, v31
	v_cvt_pk_bf16_f32 v181, v32, v33
	v_cvt_pk_bf16_f32 v184, v22, v23
	v_cvt_pk_bf16_f32 v185, v24, v25
	v_fmac_f32_e32 v203, 0, v42
	v_lshl_add_u64 v[206:207], v[38:39], 0, v[18:19]
	v_lshl_add_u64 v[208:209], v[36:37], 0, s[16:17]
	v_lshl_add_u64 v[210:211], v[34:35], 0, s[16:17]
	v_mov_b64_e32 v[32:33], v[16:17]
	v_mov_b64_e32 v[48:49], v[16:17]
	v_mov_b64_e32 v[64:65], v[16:17]
	v_mov_b64_e32 v[80:81], v[16:17]
	v_mov_b64_e32 v[96:97], v[16:17]
	v_mov_b64_e32 v[112:113], v[16:17]
	v_mov_b64_e32 v[128:129], v[16:17]
	s_add_i32 s42, s41, 4
	s_add_i32 s43, s33, 0x60
	s_mov_b32 s0, 1
	s_mov_b32 s44, 0
	s_mov_b32 s45, 3
	v_mov_b64_e32 v[30:31], v[14:15]
	v_mov_b64_e32 v[28:29], v[12:13]
	v_mov_b64_e32 v[26:27], v[10:11]
	v_mov_b64_e32 v[24:25], v[8:9]
	v_mov_b64_e32 v[22:23], v[6:7]
	v_mov_b64_e32 v[20:21], v[4:5]
	v_mov_b64_e32 v[18:19], v[2:3]
	v_mov_b64_e32 v[46:47], v[14:15]
	v_mov_b64_e32 v[44:45], v[12:13]
	v_mov_b64_e32 v[42:43], v[10:11]
	v_mov_b64_e32 v[40:41], v[8:9]
	v_mov_b64_e32 v[38:39], v[6:7]
	v_mov_b64_e32 v[36:37], v[4:5]
	v_mov_b64_e32 v[34:35], v[2:3]
	v_mov_b64_e32 v[62:63], v[14:15]
	v_mov_b64_e32 v[60:61], v[12:13]
	v_mov_b64_e32 v[58:59], v[10:11]
	v_mov_b64_e32 v[56:57], v[8:9]
	v_mov_b64_e32 v[54:55], v[6:7]
	v_mov_b64_e32 v[52:53], v[4:5]
	v_mov_b64_e32 v[50:51], v[2:3]
	v_mov_b64_e32 v[78:79], v[14:15]
	v_mov_b64_e32 v[76:77], v[12:13]
	v_mov_b64_e32 v[74:75], v[10:11]
	v_mov_b64_e32 v[72:73], v[8:9]
	v_mov_b64_e32 v[70:71], v[6:7]
	v_mov_b64_e32 v[68:69], v[4:5]
	v_mov_b64_e32 v[66:67], v[2:3]
	v_mov_b64_e32 v[94:95], v[14:15]
	v_mov_b64_e32 v[92:93], v[12:13]
	v_mov_b64_e32 v[90:91], v[10:11]
	v_mov_b64_e32 v[88:89], v[8:9]
	v_mov_b64_e32 v[86:87], v[6:7]
	v_mov_b64_e32 v[84:85], v[4:5]
	v_mov_b64_e32 v[82:83], v[2:3]
	v_mov_b64_e32 v[110:111], v[14:15]
	v_mov_b64_e32 v[108:109], v[12:13]
	v_mov_b64_e32 v[106:107], v[10:11]
	v_mov_b64_e32 v[104:105], v[8:9]
	v_mov_b64_e32 v[102:103], v[6:7]
	v_mov_b64_e32 v[100:101], v[4:5]
	v_mov_b64_e32 v[98:99], v[2:3]
	v_mov_b64_e32 v[126:127], v[14:15]
	v_mov_b64_e32 v[124:125], v[12:13]
	v_mov_b64_e32 v[122:123], v[10:11]
	v_mov_b64_e32 v[120:121], v[8:9]
	v_mov_b64_e32 v[118:119], v[6:7]
	v_mov_b64_e32 v[116:117], v[4:5]
	v_mov_b64_e32 v[114:115], v[2:3]
	s_mov_b32 s47, 0
	v_mov_b32_e32 v213, v186

.Lmy_b_nok2:
	s_waitcnt lgkmcnt(2)
	v_mfma_f32_32x32x16_bf16 v[130:145], v[248:251], v[166:169], v[130:145]
	s_waitcnt lgkmcnt(1)
	v_mfma_f32_32x32x16_bf16 v[130:145], v[214:217], v[170:173], v[130:145]
	s_waitcnt lgkmcnt(0)
	v_mfma_f32_32x32x16_bf16 v[130:145], v[188:191], v[174:177], v[130:145]
	s_lshl_b32 s3, s47, 14
	v_add_u32_e32 v252, s3, v224
	v_add_u32_e32 v253, s3, v228
	ds_read_b64_tr_b16 v[190:191], v252 offset:49152
	ds_read_b64_tr_b16 v[192:193], v252 offset:53248
	ds_read_b64_tr_b16 v[248:249], v253 offset:49152
	ds_read_b64_tr_b16 v[250:251], v253 offset:53248
	v_add_u32_e32 v254, s3, v229
	ds_read_b64_tr_b16 v[186:187], v254 offset:49152
	ds_read_b64_tr_b16 v[188:189], v254 offset:53248
	s_cmp_lt_u32 s0, s41
	s_cbranch_scc1 .LBB0_1617
	v_add_u32_e32 v0, s44, v223
	v_add_u32_e32 v214, 32, v0
	v_cmp_lt_u32_e32 vcc, v214, v201
	s_nop 1
	v_cndmask_b32_e32 v131, v246, v131, vcc
	v_cmp_le_u32_e32 vcc, v214, v201
	v_add_u32_e32 v214, 34, v0
	s_nop 0
	v_cndmask_b32_e32 v130, v246, v130, vcc
	v_cmp_le_u32_e32 vcc, v214, v201
	v_add_u32_e32 v214, 35, v0
	s_nop 0
	v_cndmask_b32_e32 v132, v246, v132, vcc
	v_cmp_le_u32_e32 vcc, v214, v201
	v_add_u32_e32 v214, 40, v0
	s_nop 0
	v_cndmask_b32_e32 v133, v246, v133, vcc
	v_cmp_le_u32_e32 vcc, v214, v201
	v_add_u32_e32 v214, 41, v0
	s_nop 0
	v_cndmask_b32_e32 v134, v246, v134, vcc
	v_cmp_le_u32_e32 vcc, v214, v201
	v_add_u32_e32 v214, 42, v0
	s_nop 0
	v_cndmask_b32_e32 v135, v246, v135, vcc
	v_cmp_le_u32_e32 vcc, v214, v201
	v_add_u32_e32 v214, 43, v0
	s_nop 0
	v_cndmask_b32_e32 v136, v246, v136, vcc
	v_cmp_le_u32_e32 vcc, v214, v201
	v_add_u32_e32 v214, 48, v0
	s_nop 0
	v_cndmask_b32_e32 v137, v246, v137, vcc
	v_cmp_le_u32_e32 vcc, v214, v201
	v_add_u32_e32 v214, 49, v0
	s_nop 0
	v_cndmask_b32_e32 v138, v246, v138, vcc
	v_cmp_le_u32_e32 vcc, v214, v201
	v_add_u32_e32 v214, 50, v0
	s_nop 0
	v_cndmask_b32_e32 v139, v246, v139, vcc
	v_cmp_le_u32_e32 vcc, v214, v201
	v_add_u32_e32 v214, 51, v0
	s_nop 0
	v_cndmask_b32_e32 v140, v246, v140, vcc
	v_cmp_le_u32_e32 vcc, v214, v201
	v_add_u32_e32 v214, 56, v0
	s_nop 0
	v_cndmask_b32_e32 v141, v246, v141, vcc
	v_cmp_le_u32_e32 vcc, v214, v201
	v_add_u32_e32 v214, 57, v0
	s_nop 0
	v_cndmask_b32_e32 v142, v246, v142, vcc
	v_cmp_le_u32_e32 vcc, v214, v201
	v_add_u32_e32 v214, 58, v0
	v_add_u32_e32 v0, 59, v0
	v_cndmask_b32_e32 v143, v246, v143, vcc
	v_cmp_le_u32_e32 vcc, v214, v201
	s_nop 1
	v_cndmask_b32_e32 v144, v246, v144, vcc
	v_cmp_le_u32_e32 vcc, v0, v201
	s_nop 1
	v_cndmask_b32_e32 v145, v246, v145, vcc
.LBB0_1617:
	s_waitcnt lgkmcnt(4)
	v_mfma_f32_32x32x16_bf16 v[114:129], v[182:185], v[190:193], v[114:129]
	v_add_u32_e32 v195, s3, v230
	ds_read_b64_tr_b16 v[190:191], v195 offset:49152
	ds_read_b64_tr_b16 v[192:193], v195 offset:53248
	v_max3_f32 v0, v130, v131, v132
	v_max3_f32 v214, v133, v134, v135
	v_max3_f32 v215, v136, v137, v138
	v_max3_f32 v216, v139, v140, v141
	s_waitcnt lgkmcnt(4)
	v_mfma_f32_32x32x16_bf16 v[98:113], v[182:185], v[248:251], v[98:113]
	ds_read_b64_tr_b16 v[248:249], v252 offset:49408
	ds_read_b64_tr_b16 v[250:251], v252 offset:53504
	v_max3_f32 v0, v0, v142, v143
	v_max3_f32 v214, v214, v144, v145
	v_max3_f32 v0, v0, v214, v215
	v_max_f32_e32 v0, v0, v216
	v_mov_b32_e32 v214, v0
	s_nop 1
	v_permlane32_swap_b32_e32 v0, v214
	v_max_f32_e32 v0, v0, v214
	s_waitcnt lgkmcnt(4)
	v_mfma_f32_32x32x16_bf16 v[82:97], v[182:185], v[186:189], v[82:97]
	ds_read_b64_tr_b16 v[186:187], v253 offset:49408
	ds_read_b64_tr_b16 v[188:189], v253 offset:53504
	v_add_f32_e32 v214, 0x41000000, v213
	v_cmp_gt_f32_e32 vcc, v0, v214
	s_cmp_eq_u64 vcc, 0
	v_max_f32_e32 v0, v213, v0
	s_cselect_b64 s[0:1], -1, 0
	v_cndmask_b32_e64 v0, v0, v213, s[0:1]
	v_sub_f32_e32 v247, v213, v0
	v_exp_f32_e32 v247, v247
	s_waitcnt lgkmcnt(4)
	v_mfma_f32_32x32x16_bf16 v[66:81], v[182:185], v[190:193], v[66:81]
	ds_read_b64_tr_b16 v[190:191], v254 offset:49408
	ds_read_b64_tr_b16 v[192:193], v254 offset:53504
	v_sub_f32_e32 v130, v130, v0
	v_exp_f32_e32 v1, v130
	v_sub_f32_e32 v131, v131, v0
	v_exp_f32_e32 v131, v131
	v_add_f32_e32 v130, 0, v1
	s_cmp_le_u32 s45, s42
	s_cbranch_scc0 .Lmy_b_nov1
	s_mov_b32 m0, s54
	s_nop 0
	global_load_lds_dwordx4 v[206:207], off
.Lmy_b_nov1:
	s_waitcnt lgkmcnt(4)
	v_mfma_f32_32x32x16_bf16 v[50:65], v[182:185], v[248:251], v[50:65]
	ds_read_b64_tr_b16 v[248:249], v195 offset:49408
	ds_read_b64_tr_b16 v[250:251], v195 offset:53504
	v_sub_f32_e32 v132, v132, v0
	v_exp_f32_e32 v132, v132
	v_add_f32_e32 v130, v131, v130
	v_sub_f32_e32 v133, v133, v0
	v_exp_f32_e32 v133, v133
	v_add_f32_e32 v130, v132, v130
	s_waitcnt lgkmcnt(4)
	v_mfma_f32_32x32x16_bf16 v[34:49], v[182:185], v[186:189], v[34:49]
	ds_read_b64_tr_b16 v[186:187], v252 offset:57344
	ds_read_b64_tr_b16 v[188:189], v252 offset:61440
	v_sub_f32_e32 v134, v134, v0
	v_exp_f32_e32 v134, v134
	v_add_f32_e32 v130, v133, v130
	v_sub_f32_e32 v135, v135, v0
	v_exp_f32_e32 v135, v135
	v_add_f32_e32 v130, v134, v130
	s_waitcnt lgkmcnt(4)
	v_mfma_f32_32x32x16_bf16 v[18:33], v[182:185], v[190:193], v[18:33]
	ds_read_b64_tr_b16 v[190:191], v253 offset:57344
	ds_read_b64_tr_b16 v[192:193], v253 offset:61440
	v_sub_f32_e32 v136, v136, v0
	v_exp_f32_e32 v136, v136
	v_add_f32_e32 v130, v135, v130
	s_waitcnt lgkmcnt(4)
	v_mfma_f32_32x32x16_bf16 v[2:17], v[182:185], v[248:251], v[2:17]
	ds_read_b64_tr_b16 v[182:183], v254 offset:57344
	ds_read_b64_tr_b16 v[184:185], v254 offset:61440
	v_sub_f32_e32 v137, v137, v0
	v_exp_f32_e32 v137, v137
	v_add_f32_e32 v130, v136, v130
	s_waitcnt lgkmcnt(4)
	v_mfma_f32_32x32x16_bf16 v[114:129], v[178:181], v[186:189], v[114:129]
	ds_read_b64_tr_b16 v[248:249], v195 offset:57344
	ds_read_b64_tr_b16 v[250:251], v195 offset:61440
	v_sub_f32_e32 v138, v138, v0
	v_exp_f32_e32 v138, v138
	v_add_f32_e32 v130, v137, v130
	s_waitcnt lgkmcnt(4)
	v_mfma_f32_32x32x16_bf16 v[98:113], v[178:181], v[190:193], v[98:113]
	ds_read_b64_tr_b16 v[190:191], v252 offset:57600
	ds_read_b64_tr_b16 v[192:193], v252 offset:61696
	v_sub_f32_e32 v139, v139, v0
	v_exp_f32_e32 v139, v139
	v_add_f32_e32 v130, v138, v130
	s_cmp_le_u32 s45, s42
	s_cbranch_scc0 .Lmy_b_nov2
	s_mov_b32 m0, s55
	s_nop 0
	global_load_lds_dwordx4 v[204:205], off

.LBB0_1619:
	v_add_f32_e32 v130, v145, v130
	s_add_i32 s0, s46, 1
	s_cmp_lg_u32 s46, 2
	s_cselect_b32 s0, s0, 0
	s_add_i32 s44, s44, 32
	s_add_i32 s45, s45, 1
	v_fmac_f32_e32 v130, v203, v247
	v_cvt_pk_bf16_f32 v182, v1, v131
	v_mov_b32_e32 v1, 0
	v_cvt_pk_bf16_f32 v183, v132, v133
	v_cvt_pk_bf16_f32 v184, v134, v135
	v_cvt_pk_bf16_f32 v185, v136, v137
	v_cvt_pk_bf16_f32 v178, v138, v139
	v_cvt_pk_bf16_f32 v179, v140, v141
	v_cvt_pk_bf16_f32 v180, v142, v143
	v_cvt_pk_bf16_f32 v181, v144, v145
	v_lshl_add_u64 v[204:205], v[204:205], 0, s[12:13]
	v_lshl_add_u64 v[206:207], v[206:207], 0, s[12:13]
	v_lshl_add_u64 v[208:209], v[208:209], 0, s[8:9]
	s_cmp_eq_u32 s43, s44
	v_lshl_add_u64 v[210:211], v[210:211], 0, s[8:9]
	s_cbranch_scc1 .LBB0_1621
	v_mov_b32_e32 v203, v130
	v_mov_b32_e32 v213, v0
	s_mov_b32 s47, s46
	s_branch .LBB0_1605
